# v041: v040 + BF16 GEMM epilogue stores as saddr form with 32-bit v_mul_u32_u24/v_lshl_add_u32 offsets instead of v_mad_i64_i32 + 64-bit adds
# baseline (speedup 1.0000x reference)
; __device__ __forceinline__ unsigned cvt_pk_bf16(float lo, float hi) { unsigned r; asm volatile("v_cvt_pk_bf16_f32 %0, %1, %2" : "=v"(r) : "v"(lo), "v"(hi)); return r; }
;     __device__ __forceinline__ void operator()(const f32x4 (&acc)[2][2][4][2], const Unit& u, int wr, int wc, int fr, int fq) const {
;         const int row0 = u.pm * BM + wr * 64 + fr, col0 = u.pn * BM + wc * 32 + 8 * fq;
;         const float sc = (u.pn * BM < qcols) ? qscale : 1.0f;
; #pragma unroll
;         for (int ai = 0; ai < 2; ++ai)
; #pragma unroll
;             for (int m = 0; m < 4; ++m)
; #pragma unroll
;                 for (int bj = 0; bj < 2; ++bj) {
;                     const f32x4 v0 = acc[ai][bj][m][0] * sc, v1 = acc[ai][bj][m][1] * sc;
;                     u32x4e w; w.x = cvt_pk_bf16(v0[0], v0[1]); w.y = cvt_pk_bf16(v0[2], v0[3]); w.z = cvt_pk_bf16(v1[0], v1[1]); w.w = cvt_pk_bf16(v1[2], v1[3]);
;                     *(u32x4e*)(O + (size_t)(row0 + ai * HALF + m * 16) * ldc + col0 + bj * HALF) = w;
;                 }
;     }
.LBB0_697:
	s_lshl_b32 s19, s57, 8
	s_cmp_lt_i32 s19, s38
	s_cselect_b64 vcc, -1, 0
	v_cndmask_b32_e32 v140, 1.0, v234, vcc
	v_lshl_add_u32 v145, s26, 8, v141
	v_or_b32_e32 v146, s19, v143
	v_pk_mul_f32 v[128:129], v[140:141], v[128:129] op_sel_hi:[0,1]
	v_pk_mul_f32 v[124:125], v[140:141], v[124:125] op_sel_hi:[0,1]
	v_ashrrev_i32_e32 v147, 31, v146
	v_pk_mul_f32 v[130:131], v[140:141], v[130:131] op_sel_hi:[0,1]
	v_pk_mul_f32 v[148:149], v[140:141], v[126:127] op_sel_hi:[0,1]
	v_cvt_pk_bf16_f32 v126, v128, v129
	v_cvt_pk_bf16_f32 v127, v130, v131
	v_cvt_pk_bf16_f32 v128, v124, v125
	v_mul_u32_u24_e32 v130, s6, v145
	v_lshlrev_b64 v[124:125], 1, v[146:147]
	v_lshl_add_u32 v130, v130, 1, v124
	v_cvt_pk_bf16_f32 v129, v148, v149
	global_store_dwordx4 v130, v[126:129], s[8:9] sc1
	v_pk_mul_f32 v[122:123], v[140:141], v[122:123] op_sel_hi:[0,1]
	v_pk_mul_f32 v[120:121], v[140:141], v[120:121] op_sel_hi:[0,1]
	v_pk_mul_f32 v[126:127], v[140:141], v[114:115] op_sel_hi:[0,1]
	v_pk_mul_f32 v[114:115], v[140:141], v[112:113] op_sel_hi:[0,1]
	v_cvt_pk_bf16_f32 v112, v120, v121
	v_cvt_pk_bf16_f32 v113, v122, v123
	v_cvt_pk_bf16_f32 v114, v114, v115
	v_cvt_pk_bf16_f32 v115, v126, v127
	global_store_dwordx4 v130, v[112:115], s[8:9] offset:256 sc1
	v_or_b32_e32 v120, 16, v145
	v_pk_mul_f32 v[106:107], v[140:141], v[106:107] op_sel_hi:[0,1]
	v_pk_mul_f32 v[112:113], v[140:141], v[118:119] op_sel_hi:[0,1]
	v_pk_mul_f32 v[114:115], v[140:141], v[116:117] op_sel_hi:[0,1]
	v_pk_mul_f32 v[116:117], v[140:141], v[110:111] op_sel_hi:[0,1]
	v_pk_mul_f32 v[110:111], v[140:141], v[108:109] op_sel_hi:[0,1]
	v_cvt_pk_bf16_f32 v108, v114, v115
	v_cvt_pk_bf16_f32 v109, v112, v113
	v_mul_u32_u24_e32 v112, s6, v120
	v_lshl_add_u32 v112, v112, 1, v124
	v_cvt_pk_bf16_f32 v110, v110, v111
	v_cvt_pk_bf16_f32 v111, v116, v117
	global_store_dwordx4 v112, v[108:111], s[8:9] sc1
	v_pk_mul_f32 v[104:105], v[140:141], v[104:105] op_sel_hi:[0,1]
	v_pk_mul_f32 v[90:91], v[140:141], v[90:91] op_sel_hi:[0,1]
	v_pk_mul_f32 v[108:109], v[140:141], v[98:99] op_sel_hi:[0,1]
	v_pk_mul_f32 v[98:99], v[140:141], v[96:97] op_sel_hi:[0,1]
	v_cvt_pk_bf16_f32 v96, v104, v105
	v_cvt_pk_bf16_f32 v97, v106, v107
	v_cvt_pk_bf16_f32 v98, v98, v99
	v_cvt_pk_bf16_f32 v99, v108, v109
	global_store_dwordx4 v112, v[96:99], s[8:9] offset:256 sc1
	v_or_b32_e32 v104, 32, v145
	v_pk_mul_f32 v[88:89], v[140:141], v[88:89] op_sel_hi:[0,1]
	v_pk_mul_f32 v[96:97], v[140:141], v[102:103] op_sel_hi:[0,1]
	v_pk_mul_f32 v[98:99], v[140:141], v[100:101] op_sel_hi:[0,1]
	v_pk_mul_f32 v[100:101], v[140:141], v[94:95] op_sel_hi:[0,1]
	v_pk_mul_f32 v[94:95], v[140:141], v[92:93] op_sel_hi:[0,1]
	v_cvt_pk_bf16_f32 v92, v98, v99
	v_cvt_pk_bf16_f32 v93, v96, v97
	v_mul_u32_u24_e32 v96, s6, v104
	v_lshl_add_u32 v96, v96, 1, v124
	v_cvt_pk_bf16_f32 v94, v94, v95
	v_cvt_pk_bf16_f32 v95, v100, v101
	global_store_dwordx4 v96, v[92:95], s[8:9] sc1
	v_pk_mul_f32 v[74:75], v[140:141], v[74:75] op_sel_hi:[0,1]
	v_pk_mul_f32 v[72:73], v[140:141], v[72:73] op_sel_hi:[0,1]
	v_pk_mul_f32 v[92:93], v[140:141], v[82:83] op_sel_hi:[0,1]
	v_pk_mul_f32 v[82:83], v[140:141], v[80:81] op_sel_hi:[0,1]
	v_cvt_pk_bf16_f32 v80, v88, v89
	v_cvt_pk_bf16_f32 v81, v90, v91
	v_cvt_pk_bf16_f32 v82, v82, v83
	v_cvt_pk_bf16_f32 v83, v92, v93
	global_store_dwordx4 v96, v[80:83], s[8:9] offset:256 sc1
	v_or_b32_e32 v88, 48, v145
	v_pk_mul_f32 v[64:65], v[140:141], v[64:65] op_sel_hi:[0,1]
	v_pk_mul_f32 v[80:81], v[140:141], v[86:87] op_sel_hi:[0,1]
	v_pk_mul_f32 v[82:83], v[140:141], v[84:85] op_sel_hi:[0,1]
	v_pk_mul_f32 v[84:85], v[140:141], v[78:79] op_sel_hi:[0,1]
	v_pk_mul_f32 v[78:79], v[140:141], v[76:77] op_sel_hi:[0,1]
	v_cvt_pk_bf16_f32 v76, v82, v83
	v_cvt_pk_bf16_f32 v77, v80, v81
	v_mul_u32_u24_e32 v80, s6, v88
	v_lshl_add_u32 v80, v80, 1, v124
	v_cvt_pk_bf16_f32 v78, v78, v79
	v_cvt_pk_bf16_f32 v79, v84, v85
	global_store_dwordx4 v80, v[76:79], s[8:9] sc1
	v_pk_mul_f32 v[66:67], v[140:141], v[66:67] op_sel_hi:[0,1]
	v_pk_mul_f32 v[58:59], v[140:141], v[58:59] op_sel_hi:[0,1]
	v_pk_mul_f32 v[76:77], v[140:141], v[70:71] op_sel_hi:[0,1]
; __device__ __forceinline__ unsigned cvt_pk_bf16(float lo, float hi) { unsigned r; asm volatile("v_cvt_pk_bf16_f32 %0, %1, %2" : "=v"(r) : "v"(lo), "v"(hi)); return r; }
;     __device__ __forceinline__ void operator()(const f32x4 (&acc)[2][2][4][2], const Unit& u, int wr, int wc, int fr, int fq) const {
;         const int row0 = u.pm * BM + wr * 64 + fr, col0 = u.pn * BM + wc * 32 + 8 * fq;
;         const float sc = (u.pn * BM < qcols) ? qscale : 1.0f;
; #pragma unroll
;         for (int ai = 0; ai < 2; ++ai)
; #pragma unroll
;             for (int m = 0; m < 4; ++m)
; #pragma unroll
;                 for (int bj = 0; bj < 2; ++bj) {
;                     const f32x4 v0 = acc[ai][bj][m][0] * sc, v1 = acc[ai][bj][m][1] * sc;
;                     u32x4e w; w.x = cvt_pk_bf16(v0[0], v0[1]); w.y = cvt_pk_bf16(v0[2], v0[3]); w.z = cvt_pk_bf16(v1[0], v1[1]); w.w = cvt_pk_bf16(v1[2], v1[3]);
;                     *(u32x4e*)(O + (size_t)(row0 + ai * HALF + m * 16) * ldc + col0 + bj * HALF) = w;
;                 }
;     }
	v_pk_mul_f32 v[70:71], v[140:141], v[68:69] op_sel_hi:[0,1]
	v_cvt_pk_bf16_f32 v68, v72, v73
	v_cvt_pk_bf16_f32 v69, v74, v75
	v_cvt_pk_bf16_f32 v70, v70, v71
	v_cvt_pk_bf16_f32 v71, v76, v77
	global_store_dwordx4 v80, v[68:71], s[8:9] offset:256 sc1
	v_pk_mul_f32 v[56:57], v[140:141], v[56:57] op_sel_hi:[0,1]
	v_pk_mul_f32 v[42:43], v[140:141], v[42:43] op_sel_hi:[0,1]
	v_add_u32_e32 v70, 0x80, v145
	v_pk_mul_f32 v[68:69], v[140:141], v[62:63] op_sel_hi:[0,1]
	v_pk_mul_f32 v[62:63], v[140:141], v[60:61] op_sel_hi:[0,1]
	v_cvt_pk_bf16_f32 v60, v64, v65
	v_mul_u32_u24_e32 v64, s6, v70
	v_cvt_pk_bf16_f32 v61, v66, v67
	v_lshl_add_u32 v64, v64, 1, v124
	v_cvt_pk_bf16_f32 v62, v62, v63
	v_cvt_pk_bf16_f32 v63, v68, v69
	global_store_dwordx4 v64, v[60:63], s[8:9] sc1
	v_pk_mul_f32 v[40:41], v[140:141], v[40:41] op_sel_hi:[0,1]
	v_pk_mul_f32 v[26:27], v[140:141], v[26:27] op_sel_hi:[0,1]
	v_pk_mul_f32 v[60:61], v[140:141], v[50:51] op_sel_hi:[0,1]
	v_pk_mul_f32 v[50:51], v[140:141], v[48:49] op_sel_hi:[0,1]
	v_cvt_pk_bf16_f32 v48, v56, v57
	v_cvt_pk_bf16_f32 v49, v58, v59
	v_cvt_pk_bf16_f32 v50, v50, v51
	v_cvt_pk_bf16_f32 v51, v60, v61
	global_store_dwordx4 v64, v[48:51], s[8:9] offset:256 sc1
	v_add_u32_e32 v56, 0x90, v145
	v_pk_mul_f32 v[24:25], v[140:141], v[24:25] op_sel_hi:[0,1]
	v_pk_mul_f32 v[48:49], v[140:141], v[54:55] op_sel_hi:[0,1]
	v_pk_mul_f32 v[50:51], v[140:141], v[52:53] op_sel_hi:[0,1]
	v_pk_mul_f32 v[52:53], v[140:141], v[46:47] op_sel_hi:[0,1]
	v_pk_mul_f32 v[46:47], v[140:141], v[44:45] op_sel_hi:[0,1]
	v_cvt_pk_bf16_f32 v44, v50, v51
	v_cvt_pk_bf16_f32 v45, v48, v49
	v_mul_u32_u24_e32 v48, s6, v56
	v_lshl_add_u32 v48, v48, 1, v124
	v_cvt_pk_bf16_f32 v46, v46, v47
	v_cvt_pk_bf16_f32 v47, v52, v53
	global_store_dwordx4 v48, v[44:47], s[8:9] sc1
	s_andn2_b64 vcc, exec, s[0:1]
	s_mov_b64 s[0:1], -1
	v_pk_mul_f32 v[44:45], v[140:141], v[34:35] op_sel_hi:[0,1]
	v_pk_mul_f32 v[34:35], v[140:141], v[32:33] op_sel_hi:[0,1]
	v_cvt_pk_bf16_f32 v32, v40, v41
	v_cvt_pk_bf16_f32 v33, v42, v43
	v_cvt_pk_bf16_f32 v34, v34, v35
	v_cvt_pk_bf16_f32 v35, v44, v45
	global_store_dwordx4 v48, v[32:35], s[8:9] offset:256 sc1
	v_add_u32_e32 v40, 0xa0, v145
	v_pk_mul_f32 v[10:11], v[140:141], v[10:11] op_sel_hi:[0,1]
	v_pk_mul_f32 v[32:33], v[140:141], v[38:39] op_sel_hi:[0,1]
	v_pk_mul_f32 v[34:35], v[140:141], v[36:37] op_sel_hi:[0,1]
	v_pk_mul_f32 v[36:37], v[140:141], v[30:31] op_sel_hi:[0,1]
	v_pk_mul_f32 v[30:31], v[140:141], v[28:29] op_sel_hi:[0,1]
	v_cvt_pk_bf16_f32 v28, v34, v35
	v_cvt_pk_bf16_f32 v29, v32, v33
	v_mul_u32_u24_e32 v32, s6, v40
	v_lshl_add_u32 v32, v32, 1, v124
	v_cvt_pk_bf16_f32 v30, v30, v31
	v_cvt_pk_bf16_f32 v31, v36, v37
	global_store_dwordx4 v32, v[28:31], s[8:9] sc1
	v_pk_mul_f32 v[8:9], v[140:141], v[8:9] op_sel_hi:[0,1]
	s_nop 0
	v_pk_mul_f32 v[28:29], v[140:141], v[18:19] op_sel_hi:[0,1]
	v_pk_mul_f32 v[18:19], v[140:141], v[16:17] op_sel_hi:[0,1]
	v_cvt_pk_bf16_f32 v16, v24, v25
	v_cvt_pk_bf16_f32 v17, v26, v27
	v_cvt_pk_bf16_f32 v18, v18, v19
	v_cvt_pk_bf16_f32 v19, v28, v29
	global_store_dwordx4 v32, v[16:19], s[8:9] offset:256 sc1
	v_add_u32_e32 v24, 0xb0, v145
	s_nop 0
	v_pk_mul_f32 v[16:17], v[140:141], v[22:23] op_sel_hi:[0,1]
	v_pk_mul_f32 v[18:19], v[140:141], v[20:21] op_sel_hi:[0,1]
	v_pk_mul_f32 v[20:21], v[140:141], v[14:15] op_sel_hi:[0,1]
	v_pk_mul_f32 v[14:15], v[140:141], v[12:13] op_sel_hi:[0,1]
	v_cvt_pk_bf16_f32 v12, v18, v19
	v_cvt_pk_bf16_f32 v13, v16, v17
	v_mul_u32_u24_e32 v16, s6, v24
	v_lshl_add_u32 v16, v16, 1, v124
	v_cvt_pk_bf16_f32 v14, v14, v15
	v_cvt_pk_bf16_f32 v15, v20, v21
	global_store_dwordx4 v16, v[12:15], s[8:9] sc1
	s_nop 1
	v_pk_mul_f32 v[12:13], v[140:141], v[6:7] op_sel_hi:[0,1]
	v_pk_mul_f32 v[6:7], v[140:141], v[4:5] op_sel_hi:[0,1]
	v_cvt_pk_bf16_f32 v4, v8, v9
	v_cvt_pk_bf16_f32 v5, v10, v11
	v_cvt_pk_bf16_f32 v6, v6, v7
	v_cvt_pk_bf16_f32 v7, v12, v13
	global_store_dwordx4 v16, v[4:7], s[8:9] offset:256 sc1
	s_cbranch_vccnz .LBB0_686
	s_andn2_b64 vcc, exec, s[14:15]
	s_cbranch_vccnz .LBB0_685
	s_barrier
	s_branch .LBB0_685
